# k24 + T1/T3 wave reductions via DPP adds and v_permlane16_swap instead of ds_swizzle round trips
# speedup vs baseline: 1.0082x; 1.0025x over previous
; #define GASF __attribute__((address_space(1)))
; __device__ __forceinline__ float wave_sum(float v) {
;     v += swz_xor<1>(v); v += swz_xor<2>(v); v += swz_xor<4>(v); v += swz_xor<8>(v); v += swz_xor<16>(v);
; __device__ __forceinline__ void resid_rows(const float* xf_, bf16_t* XB_, const bf16_t* Y_, const float* gain_, float* R_, float* outf_, int rows, int gw, int NGW, int lane) {
;     ...
;         if (Y_) { float y[16]; float ss = 0.f;
; #pragma unroll
;             for (int j = 0; j < 2; ++j) { const u32x4 w = yw[j];
;                 y[8 * j + 0] = bf_lo(w.x); y[8 * j + 1] = bf_hi(w.x); y[8 * j + 2] = bf_lo(w.y); y[8 * j + 3] = bf_hi(w.y); y[8 * j + 4] = bf_lo(w.z); y[8 * j + 5] = bf_hi(w.z); y[8 * j + 6] = bf_lo(w.w); y[8 * j + 7] = bf_hi(w.w); }
; #pragma unroll
;             for (int i = 0; i < 16; ++i) ss += y[i] * y[i];
;             const float r = 1.0f / sqrtf(wave_sum(ss) * (1.f / DM) + EPS);
;             const GASF f32x4* gp = (const GASF f32x4*)gain_;
; #pragma unroll
;             for (int j = 0; j < 2; ++j) { const f32x4 a = gp[lane * 2 + 128 * j], b = gp[lane * 2 + 1 + 128 * j];
;                 v[8 * j + 0] += y[8 * j + 0] * r * a.x; v[8 * j + 1] += y[8 * j + 1] * r * a.y; v[8 * j + 2] += y[8 * j + 2] * r * a.z; v[8 * j + 3] += y[8 * j + 3] * r * a.w;
;                 v[8 * j + 4] += y[8 * j + 4] * r * b.x; v[8 * j + 5] += y[8 * j + 5] * r * b.y; v[8 * j + 6] += y[8 * j + 6] * r * b.z; v[8 * j + 7] += y[8 * j + 7] * r * b.w; } }
;         if (outf_) { GASF f32x4* p = (GASF f32x4*)(outf_ + (size_t)row * DM);
; #pragma unroll
;             for (int j = 0; j < 2; ++j) { p[lane * 2 + 128 * j] = (f32x4){v[8 * j + 0], v[8 * j + 1], v[8 * j + 2], v[8 * j + 3]}; p[lane * 2 + 1 + 128 * j] = (f32x4){v[8 * j + 4], v[8 * j + 5], v[8 * j + 6], v[8 * j + 7]}; } }
;         else { GASF u32x4* p = (GASF u32x4*)(XB_ + (size_t)row * DM); float ss = 0.f;
; #pragma unroll
;             for (int i = 0; i < 16; ++i) ss += v[i] * v[i];
; #pragma unroll
;             for (int j = 0; j < 2; ++j) { u32x4 w; w.x = cvt_pk_bf16(v[8 * j + 0], v[8 * j + 1]); w.y = cvt_pk_bf16(v[8 * j + 2], v[8 * j + 3]); w.z = cvt_pk_bf16(v[8 * j + 4], v[8 * j + 5]); w.w = cvt_pk_bf16(v[8 * j + 6], v[8 * j + 7]); p[lane + 64 * j] = w; }
;             ss = wave_sum(ss);
;             if (lane == 0) ((GASF float*)R_)[row] = 1.0f / sqrtf(ss * (1.f / DM) + EPS); }
.LBB0_199:
	s_waitcnt vmcnt(3)
	v_mov_b64_e32 v[18:19], v[14:15]
	v_mov_b64_e32 v[16:17], v[12:13]
	v_and_b32_e32 v54, 0xffff0000, v16
	v_lshlrev_b32_e32 v53, 16, v16
	v_mul_f32_e32 v16, v54, v54
	v_lshlrev_b32_e32 v55, 16, v17
	v_fmac_f32_e32 v16, v53, v53
	v_and_b32_e32 v56, 0xffff0000, v17
	v_fmac_f32_e32 v16, v55, v55
	v_lshlrev_b32_e32 v57, 16, v18
	v_fmac_f32_e32 v16, v56, v56
	v_and_b32_e32 v58, 0xffff0000, v18
	v_fmac_f32_e32 v16, v57, v57
	v_mov_b64_e32 v[22:23], v[6:7]
	v_lshlrev_b32_e32 v59, 16, v19
	v_fmac_f32_e32 v16, v58, v58
	v_mov_b64_e32 v[20:21], v[4:5]
	v_and_b32_e32 v60, 0xffff0000, v19
	v_fmac_f32_e32 v16, v59, v59
	v_lshlrev_b32_e32 v51, 16, v20
	v_fmac_f32_e32 v16, v60, v60
	v_and_b32_e32 v50, 0xffff0000, v20
	v_fmac_f32_e32 v16, v51, v51
	v_mov_b64_e32 v[30:31], v[10:11]
	v_lshlrev_b32_e32 v49, 16, v21
	v_fmac_f32_e32 v16, v50, v50
	v_mov_b64_e32 v[28:29], v[8:9]
	v_mov_b64_e32 v[46:47], v[2:3]
	v_and_b32_e32 v48, 0xffff0000, v21
	v_fmac_f32_e32 v16, v49, v49
	v_lshlrev_b32_e32 v41, 16, v28
	v_and_b32_e32 v43, 0xffff0000, v28
	v_lshlrev_b32_e32 v42, 16, v29
	v_and_b32_e32 v40, 0xffff0000, v29
	v_lshlrev_b32_e32 v29, 16, v47
	v_and_b32_e32 v28, 0xffff0000, v47
	v_lshlrev_b32_e32 v47, 16, v22
	v_fmac_f32_e32 v16, v48, v48
	v_mov_b64_e32 v[44:45], v[0:1]
	v_lshlrev_b32_e32 v39, 16, v30
	v_and_b32_e32 v38, 0xffff0000, v30
	v_lshlrev_b32_e32 v37, 16, v31
	v_and_b32_e32 v36, 0xffff0000, v31
	v_lshlrev_b32_e32 v31, 16, v46
	v_and_b32_e32 v30, 0xffff0000, v46
	v_and_b32_e32 v46, 0xffff0000, v22
	v_fmac_f32_e32 v16, v47, v47
	v_lshlrev_b32_e32 v33, 16, v45
	v_and_b32_e32 v32, 0xffff0000, v45
	v_lshlrev_b32_e32 v45, 16, v23
	v_fmac_f32_e32 v16, v46, v46
	v_lshlrev_b32_e32 v35, 16, v44
	v_and_b32_e32 v34, 0xffff0000, v44
	v_and_b32_e32 v44, 0xffff0000, v23
	v_fmac_f32_e32 v16, v45, v45
	v_fmac_f32_e32 v16, v44, v44
	s_add_i32 s1, s1, s2
	s_min_i32 s28, s1, 0x7fff
	s_ashr_i32 s29, s28, 31
	s_lshl_b64 s[28:29], s[28:29], 11
	s_nop 1
	v_add_f32_dpp v16, v16, v16 quad_perm:[1,0,3,2] row_mask:0xf bank_mask:0xf
	s_add_u32 s30, s4, s28
	s_addc_u32 s31, s5, s29
	s_add_u32 s28, s7, s28
	s_addc_u32 s29, s8, s29
	s_nop 1
	v_add_f32_dpp v16, v16, v16 quad_perm:[2,3,0,1] row_mask:0xf bank_mask:0xf
	v_lshl_add_u64 v[4:5], s[28:29], 0, v[24:25]
	v_lshl_add_u64 v[0:1], s[30:31], 0, v[24:25]
	global_load_dwordx4 v[8:11], v[0:1], off
	s_nop 0
	global_load_dwordx4 v[0:3], v[0:1], off offset:1024
	s_nop 0
	global_load_dwordx4 v[12:15], v[4:5], off
	s_nop 0
	global_load_dwordx4 v[4:7], v[4:5], off offset:1024
	s_nop 1
	v_add_f32_dpp v16, v16, v16 row_half_mirror row_mask:0xf bank_mask:0xf
	s_nop 1
	v_add_f32_dpp v16, v16, v16 row_mirror row_mask:0xf bank_mask:0xf
	v_mov_b32_e32 v17, v16
	s_nop 1
	v_permlane16_swap_b32_e32 v16, v17
	v_add_f32_e32 v16, v16, v17
	v_mov_b32_e32 v17, v16
	s_nop 1
	v_permlane32_swap_b32_e32 v16, v17
	v_add_f32_e32 v16, v16, v17
	v_fmamk_f32 v16, v16, 0x3a800000, v204
	v_cmp_gt_f32_e32 vcc, s81, v16
	v_mul_f32_e32 v17, 0x4f800000, v16
	s_nop 0
	v_cndmask_b32_e32 v16, v16, v17, vcc
	v_sqrt_f32_e32 v17, v16
	s_nop 0
	v_add_u32_e32 v18, -1, v17
	v_fma_f32 v19, -v18, v17, v16
	v_cmp_ge_f32_e64 s[42:43], 0, v19
	v_add_u32_e32 v19, 1, v17
	s_nop 0
	v_cndmask_b32_e64 v18, v17, v18, s[42:43]
	v_fma_f32 v17, -v19, v17, v16
	v_cmp_lt_f32_e64 s[42:43], 0, v17
	s_nop 1
	v_cndmask_b32_e64 v17, v18, v19, s[42:43]
	v_mul_f32_e32 v18, 0x37800000, v17
	v_cndmask_b32_e32 v17, v17, v18, vcc
	v_cmp_class_f32_e32 vcc, v16, v205
	s_nop 1
	v_cndmask_b32_e32 v16, v17, v16, vcc
	v_div_scale_f32 v17, s[28:29], v16, v16, 1.0
	v_rcp_f32_e32 v18, v17
	s_nop 0
	v_fma_f32 v19, -v17, v18, 1.0
	v_fmac_f32_e32 v18, v19, v18
	v_div_scale_f32 v19, vcc, 1.0, v16, 1.0
	v_mul_f32_e32 v20, v19, v18
	v_fma_f32 v21, -v17, v20, v19
	v_fmac_f32_e32 v20, v21, v18
	v_fma_f32 v17, -v17, v20, v19
	v_div_fmas_f32 v17, v17, v18, v20
	v_div_fixup_f32 v52, v17, v16, 1.0
	v_mul_f32_e32 v53, v52, v53
	v_mul_f32_e32 v51, v52, v51
	v_fmac_f32_e32 v41, v68, v53
	v_mul_f32_e32 v20, v52, v54
	v_fmac_f32_e32 v43, v69, v20
	v_mul_f32_e32 v20, v52, v55
	v_fmac_f32_e32 v42, v70, v20
	v_mul_f32_e32 v20, v52, v56
	v_fmac_f32_e32 v40, v71, v20
	v_mul_f32_e32 v20, v52, v57
	v_fmac_f32_e32 v39, v72, v20
	v_mul_f32_e32 v16, v52, v58
	v_fmac_f32_e32 v38, v73, v16
	v_mul_f32_e32 v16, v52, v59
	v_fmac_f32_e32 v37, v74, v16
	v_mul_f32_e32 v16, v52, v60
	v_fmac_f32_e32 v36, v75, v16
	v_fmac_f32_e32 v35, v76, v51
	v_mul_f32_e32 v20, v52, v50
	v_fmac_f32_e32 v34, v77, v20
	v_mul_f32_e32 v20, v52, v49
	v_fmac_f32_e32 v33, v78, v20
	v_mul_f32_e32 v22, v43, v43
	v_fmac_f32_e32 v22, v41, v41
	v_fmac_f32_e32 v22, v42, v42
	v_fmac_f32_e32 v22, v40, v40
	v_fmac_f32_e32 v22, v39, v39
	v_fmac_f32_e32 v22, v38, v38
	v_fmac_f32_e32 v22, v37, v37
	v_fmac_f32_e32 v22, v36, v36
	v_fmac_f32_e32 v22, v35, v35
	v_mul_f32_e32 v20, v52, v48
	v_fmac_f32_e32 v22, v34, v34
	v_fmac_f32_e32 v32, v79, v20
	v_mul_f32_e32 v20, v52, v47
	v_fmac_f32_e32 v22, v33, v33
	v_fmac_f32_e32 v31, v80, v20
	v_mul_f32_e32 v16, v52, v46
	v_fmac_f32_e32 v22, v32, v32
	v_fmac_f32_e32 v30, v81, v16
	v_mul_f32_e32 v16, v52, v45
	v_fmac_f32_e32 v22, v31, v31
	v_fmac_f32_e32 v29, v82, v16
	v_mul_f32_e32 v16, v52, v44
	v_fmac_f32_e32 v22, v30, v30
	v_fmac_f32_e32 v28, v83, v16
	v_cvt_pk_bf16_f32 v16, v41, v43
	v_lshl_add_u64 v[20:21], s[16:17], 0, v[24:25]
	v_fmac_f32_e32 v22, v29, v29
	v_cvt_pk_bf16_f32 v17, v42, v40
	v_cvt_pk_bf16_f32 v18, v39, v38
	v_cvt_pk_bf16_f32 v19, v37, v36
	global_store_dwordx4 v[20:21], v[16:19], off
	v_fmac_f32_e32 v22, v28, v28
	s_nop 0
	v_cvt_pk_bf16_f32 v16, v35, v34
	v_cvt_pk_bf16_f32 v17, v33, v32
	v_cvt_pk_bf16_f32 v18, v31, v30
	v_cvt_pk_bf16_f32 v19, v29, v28
	global_store_dwordx4 v[20:21], v[16:19], off offset:1024
	s_nop 1
	v_add_f32_dpp v16, v22, v22 quad_perm:[1,0,3,2] row_mask:0xf bank_mask:0xf
	s_nop 1
	v_add_f32_dpp v16, v16, v16 quad_perm:[2,3,0,1] row_mask:0xf bank_mask:0xf
	s_nop 1
	v_add_f32_dpp v16, v16, v16 row_half_mirror row_mask:0xf bank_mask:0xf
	s_nop 1
	v_add_f32_dpp v16, v16, v16 row_mirror row_mask:0xf bank_mask:0xf
	v_mov_b32_e32 v17, v16
	s_nop 1
	v_permlane16_swap_b32_e32 v16, v17
	v_add_f32_e32 v16, v16, v17
	v_mov_b32_e32 v17, v16
	s_nop 1
	v_permlane32_swap_b32_e32 v16, v17
	s_and_saveexec_b64 s[28:29], s[40:41]
	s_cbranch_execz .LBB0_198
; #define GASF __attribute__((address_space(1)))
; __device__ __forceinline__ void resid_rows(const float* xf_, bf16_t* XB_, const bf16_t* Y_, const float* gain_, float* R_, float* outf_, int rows, int gw, int NGW, int lane) {
;     ...
;             ss = wave_sum(ss);
;             if (lane == 0) ((GASF float*)R_)[row] = 1.0f / sqrtf(ss * (1.f / DM) + EPS); }
	v_add_f32_e32 v16, v16, v17
	v_fmamk_f32 v16, v16, 0x3a800000, v204
	v_mul_f32_e32 v17, 0x4f800000, v16
	v_cmp_gt_f32_e32 vcc, s81, v16
	s_nop 1
	v_cndmask_b32_e32 v16, v16, v17, vcc
	v_sqrt_f32_e32 v17, v16
	s_nop 0
	v_add_u32_e32 v18, -1, v17
	v_fma_f32 v20, -v18, v17, v16
	v_add_u32_e32 v19, 1, v17
	v_cmp_ge_f32_e64 s[42:43], 0, v20
	s_nop 1
	v_cndmask_b32_e64 v18, v17, v18, s[42:43]
	v_fma_f32 v17, -v19, v17, v16
	v_cmp_lt_f32_e64 s[42:43], 0, v17
	s_nop 1
	v_cndmask_b32_e64 v17, v18, v19, s[42:43]
	v_mul_f32_e32 v18, 0x37800000, v17
	v_cndmask_b32_e32 v17, v17, v18, vcc
	v_cmp_class_f32_e32 vcc, v16, v205
	s_nop 1
	v_cndmask_b32_e32 v16, v17, v16, vcc
	v_div_scale_f32 v17, s[30:31], v16, v16, 1.0
	v_rcp_f32_e32 v18, v17
	s_nop 0
	v_fma_f32 v19, -v17, v18, 1.0
	v_fmac_f32_e32 v18, v19, v18
	v_div_scale_f32 v19, vcc, 1.0, v16, 1.0
	v_mul_f32_e32 v20, v19, v18
	v_fma_f32 v21, -v17, v20, v19
	v_fmac_f32_e32 v20, v21, v18
	v_fma_f32 v17, -v17, v20, v19
	v_div_fmas_f32 v17, v17, v18, v20
	v_div_fixup_f32 v16, v17, v16, 1.0
	global_store_dword v175, v16, s[18:19]
	s_branch .LBB0_198

; #define GASF __attribute__((address_space(1)))
; __device__ __forceinline__ float wave_sum(float v) {
;     v += swz_xor<1>(v); v += swz_xor<2>(v); v += swz_xor<4>(v); v += swz_xor<8>(v); v += swz_xor<16>(v);
; __device__ __forceinline__ void resid_rows(const float* xf_, bf16_t* XB_, const bf16_t* Y_, const float* gain_, float* R_, float* outf_, int rows, int gw, int NGW, int lane) {
;     ...
;         if (Y_) { float y[16]; float ss = 0.f;
; #pragma unroll
;             for (int j = 0; j < 2; ++j) { const u32x4 w = yw[j];
;                 y[8 * j + 0] = bf_lo(w.x); y[8 * j + 1] = bf_hi(w.x); y[8 * j + 2] = bf_lo(w.y); y[8 * j + 3] = bf_hi(w.y); y[8 * j + 4] = bf_lo(w.z); y[8 * j + 5] = bf_hi(w.z); y[8 * j + 6] = bf_lo(w.w); y[8 * j + 7] = bf_hi(w.w); }
; #pragma unroll
;             for (int i = 0; i < 16; ++i) ss += y[i] * y[i];
;             const float r = 1.0f / sqrtf(wave_sum(ss) * (1.f / DM) + EPS);
;             const GASF f32x4* gp = (const GASF f32x4*)gain_;
; #pragma unroll
;             for (int j = 0; j < 2; ++j) { const f32x4 a = gp[lane * 2 + 128 * j], b = gp[lane * 2 + 1 + 128 * j];
;                 v[8 * j + 0] += y[8 * j + 0] * r * a.x; v[8 * j + 1] += y[8 * j + 1] * r * a.y; v[8 * j + 2] += y[8 * j + 2] * r * a.z; v[8 * j + 3] += y[8 * j + 3] * r * a.w;
;                 v[8 * j + 4] += y[8 * j + 4] * r * b.x; v[8 * j + 5] += y[8 * j + 5] * r * b.y; v[8 * j + 6] += y[8 * j + 6] * r * b.z; v[8 * j + 7] += y[8 * j + 7] * r * b.w; } }
;         if (outf_) { GASF f32x4* p = (GASF f32x4*)(outf_ + (size_t)row * DM);
; #pragma unroll
;             for (int j = 0; j < 2; ++j) { p[lane * 2 + 128 * j] = (f32x4){v[8 * j + 0], v[8 * j + 1], v[8 * j + 2], v[8 * j + 3]}; p[lane * 2 + 1 + 128 * j] = (f32x4){v[8 * j + 4], v[8 * j + 5], v[8 * j + 6], v[8 * j + 7]}; } }
;         else { GASF u32x4* p = (GASF u32x4*)(XB_ + (size_t)row * DM); float ss = 0.f;
; #pragma unroll
;             for (int i = 0; i < 16; ++i) ss += v[i] * v[i];
; #pragma unroll
;             for (int j = 0; j < 2; ++j) { u32x4 w; w.x = cvt_pk_bf16(v[8 * j + 0], v[8 * j + 1]); w.y = cvt_pk_bf16(v[8 * j + 2], v[8 * j + 3]); w.z = cvt_pk_bf16(v[8 * j + 4], v[8 * j + 5]); w.w = cvt_pk_bf16(v[8 * j + 6], v[8 * j + 7]); p[lane + 64 * j] = w; }
;             ss = wave_sum(ss);
;             if (lane == 0) ((GASF float*)R_)[row] = 1.0f / sqrtf(ss * (1.f / DM) + EPS); }
.LBB0_1269:
	s_waitcnt vmcnt(3)
	v_mov_b64_e32 v[18:19], v[14:15]
	v_mov_b64_e32 v[16:17], v[12:13]
	v_and_b32_e32 v54, 0xffff0000, v16
	v_lshlrev_b32_e32 v53, 16, v16
	v_mul_f32_e32 v16, v54, v54
	v_lshlrev_b32_e32 v55, 16, v17
	v_fmac_f32_e32 v16, v53, v53
	v_and_b32_e32 v56, 0xffff0000, v17
	v_fmac_f32_e32 v16, v55, v55
	v_lshlrev_b32_e32 v57, 16, v18
	v_fmac_f32_e32 v16, v56, v56
	v_and_b32_e32 v58, 0xffff0000, v18
	v_fmac_f32_e32 v16, v57, v57
	v_mov_b64_e32 v[22:23], v[10:11]
	v_lshlrev_b32_e32 v59, 16, v19
	v_fmac_f32_e32 v16, v58, v58
	v_mov_b64_e32 v[20:21], v[8:9]
	v_and_b32_e32 v60, 0xffff0000, v19
	v_fmac_f32_e32 v16, v59, v59
	v_lshlrev_b32_e32 v51, 16, v20
	v_fmac_f32_e32 v16, v60, v60
	v_and_b32_e32 v50, 0xffff0000, v20
	v_fmac_f32_e32 v16, v51, v51
	s_nop 0
	v_mov_b64_e32 v[30:31], v[6:7]
	v_lshlrev_b32_e32 v49, 16, v21
	v_fmac_f32_e32 v16, v50, v50
	v_mov_b64_e32 v[28:29], v[4:5]
	v_mov_b64_e32 v[46:47], v[2:3]
	v_and_b32_e32 v48, 0xffff0000, v21
	v_fmac_f32_e32 v16, v49, v49
	v_lshlrev_b32_e32 v41, 16, v28
	v_and_b32_e32 v43, 0xffff0000, v28
	v_lshlrev_b32_e32 v42, 16, v29
	v_and_b32_e32 v40, 0xffff0000, v29
	v_lshlrev_b32_e32 v29, 16, v47
	v_and_b32_e32 v28, 0xffff0000, v47
	v_lshlrev_b32_e32 v47, 16, v22
	v_fmac_f32_e32 v16, v48, v48
	v_mov_b64_e32 v[44:45], v[0:1]
	v_lshlrev_b32_e32 v39, 16, v30
	v_and_b32_e32 v38, 0xffff0000, v30
	v_lshlrev_b32_e32 v37, 16, v31
	v_and_b32_e32 v36, 0xffff0000, v31
	v_lshlrev_b32_e32 v31, 16, v46
	v_and_b32_e32 v30, 0xffff0000, v46
	v_and_b32_e32 v46, 0xffff0000, v22
	v_fmac_f32_e32 v16, v47, v47
	v_lshlrev_b32_e32 v33, 16, v45
	v_and_b32_e32 v32, 0xffff0000, v45
	v_lshlrev_b32_e32 v45, 16, v23
	v_fmac_f32_e32 v16, v46, v46
	v_lshlrev_b32_e32 v35, 16, v44
	v_and_b32_e32 v34, 0xffff0000, v44
	v_and_b32_e32 v44, 0xffff0000, v23
	v_fmac_f32_e32 v16, v45, v45
	v_fmac_f32_e32 v16, v44, v44
	s_add_i32 s0, s0, s2
	s_min_i32 s20, s0, 0x7fff
	s_ashr_i32 s21, s20, 31
	s_lshl_b64 s[20:21], s[20:21], 11
	s_nop 1
	v_add_f32_dpp v16, v16, v16 quad_perm:[1,0,3,2] row_mask:0xf bank_mask:0xf
	s_add_u32 s28, s4, s20
	s_addc_u32 s29, s7, s21
	s_add_u32 s20, s8, s20
	s_addc_u32 s21, s22, s21
	s_nop 1
	v_add_f32_dpp v16, v16, v16 quad_perm:[2,3,0,1] row_mask:0xf bank_mask:0xf
	v_lshl_add_u64 v[8:9], s[20:21], 0, v[24:25]
	v_lshl_add_u64 v[0:1], s[28:29], 0, v[24:25]
	global_load_dwordx4 v[4:7], v[0:1], off
	s_nop 0
	global_load_dwordx4 v[0:3], v[0:1], off offset:1024
	s_nop 0
	global_load_dwordx4 v[12:15], v[8:9], off
	s_nop 0
	global_load_dwordx4 v[8:11], v[8:9], off offset:1024
	s_nop 1
	v_add_f32_dpp v16, v16, v16 row_half_mirror row_mask:0xf bank_mask:0xf
	s_nop 1
	v_add_f32_dpp v16, v16, v16 row_mirror row_mask:0xf bank_mask:0xf
	v_mov_b32_e32 v17, v16
	s_nop 1
	v_permlane16_swap_b32_e32 v16, v17
	v_add_f32_e32 v16, v16, v17
	v_mov_b32_e32 v17, v16
	s_nop 1
	v_permlane32_swap_b32_e32 v16, v17
	v_add_f32_e32 v16, v16, v17
	v_fmamk_f32 v16, v16, 0x3a800000, v204
	v_cmp_gt_f32_e32 vcc, s81, v16
	v_mul_f32_e32 v17, 0x4f800000, v16
	s_nop 0
	v_cndmask_b32_e32 v16, v16, v17, vcc
	v_sqrt_f32_e32 v17, v16
	s_nop 0
	v_add_u32_e32 v18, -1, v17
	v_fma_f32 v19, -v18, v17, v16
	v_cmp_ge_f32_e64 s[42:43], 0, v19
	v_add_u32_e32 v19, 1, v17
	s_nop 0
	v_cndmask_b32_e64 v18, v17, v18, s[42:43]
	v_fma_f32 v17, -v19, v17, v16
	v_cmp_lt_f32_e64 s[42:43], 0, v17
	s_nop 1
	v_cndmask_b32_e64 v17, v18, v19, s[42:43]
	v_mul_f32_e32 v18, 0x37800000, v17
	v_cndmask_b32_e32 v17, v17, v18, vcc
	v_cmp_class_f32_e32 vcc, v16, v205
	s_nop 1
	v_cndmask_b32_e32 v16, v17, v16, vcc
	v_div_scale_f32 v17, s[20:21], v16, v16, 1.0
	v_rcp_f32_e32 v18, v17
	s_nop 0
	v_fma_f32 v19, -v17, v18, 1.0
	v_fmac_f32_e32 v18, v19, v18
	v_div_scale_f32 v19, vcc, 1.0, v16, 1.0
	v_mul_f32_e32 v20, v19, v18
	v_fma_f32 v21, -v17, v20, v19
	v_fmac_f32_e32 v20, v21, v18
	v_fma_f32 v17, -v17, v20, v19
	v_div_fmas_f32 v17, v17, v18, v20
	v_div_fixup_f32 v52, v17, v16, 1.0
	v_mul_f32_e32 v53, v52, v53
	v_mul_f32_e32 v51, v52, v51
	v_fmac_f32_e32 v41, v68, v53
	v_mul_f32_e32 v20, v52, v54
	v_fmac_f32_e32 v43, v69, v20
	v_mul_f32_e32 v20, v52, v55
	v_fmac_f32_e32 v42, v70, v20
	v_mul_f32_e32 v20, v52, v56
	v_fmac_f32_e32 v40, v71, v20
	v_mul_f32_e32 v20, v52, v57
	v_fmac_f32_e32 v39, v72, v20
	v_mul_f32_e32 v16, v52, v58
	v_fmac_f32_e32 v38, v73, v16
	v_mul_f32_e32 v16, v52, v59
	v_fmac_f32_e32 v37, v74, v16
	v_mul_f32_e32 v16, v52, v60
	v_fmac_f32_e32 v36, v75, v16
	v_fmac_f32_e32 v35, v76, v51
	v_mul_f32_e32 v20, v52, v50
	v_fmac_f32_e32 v34, v77, v20
	v_mul_f32_e32 v20, v52, v49
	v_fmac_f32_e32 v33, v78, v20
	v_mul_f32_e32 v22, v43, v43
	v_fmac_f32_e32 v22, v41, v41
	v_fmac_f32_e32 v22, v42, v42
	v_fmac_f32_e32 v22, v40, v40
	v_fmac_f32_e32 v22, v39, v39
	v_fmac_f32_e32 v22, v38, v38
	v_fmac_f32_e32 v22, v37, v37
	v_fmac_f32_e32 v22, v36, v36
	v_fmac_f32_e32 v22, v35, v35
	v_mul_f32_e32 v20, v52, v48
	v_fmac_f32_e32 v22, v34, v34
	v_fmac_f32_e32 v32, v79, v20
	v_mul_f32_e32 v20, v52, v47
	v_fmac_f32_e32 v22, v33, v33
	v_fmac_f32_e32 v31, v80, v20
	v_mul_f32_e32 v16, v52, v46
	v_fmac_f32_e32 v22, v32, v32
	v_fmac_f32_e32 v30, v81, v16
	v_mul_f32_e32 v16, v52, v45
	v_fmac_f32_e32 v22, v31, v31
	v_fmac_f32_e32 v29, v82, v16
	v_mul_f32_e32 v16, v52, v44
	v_fmac_f32_e32 v22, v30, v30
	v_fmac_f32_e32 v28, v83, v16
	v_cvt_pk_bf16_f32 v16, v41, v43
	v_lshl_add_u64 v[20:21], s[16:17], 0, v[24:25]
	v_fmac_f32_e32 v22, v29, v29
	v_cvt_pk_bf16_f32 v17, v42, v40
	v_cvt_pk_bf16_f32 v18, v39, v38
	v_cvt_pk_bf16_f32 v19, v37, v36
	global_store_dwordx4 v[20:21], v[16:19], off
	v_fmac_f32_e32 v22, v28, v28
	s_nop 0
	v_cvt_pk_bf16_f32 v16, v35, v34
	v_cvt_pk_bf16_f32 v17, v33, v32
	v_cvt_pk_bf16_f32 v18, v31, v30
	v_cvt_pk_bf16_f32 v19, v29, v28
	global_store_dwordx4 v[20:21], v[16:19], off offset:1024
	s_nop 1
	v_add_f32_dpp v16, v22, v22 quad_perm:[1,0,3,2] row_mask:0xf bank_mask:0xf
	s_nop 1
	v_add_f32_dpp v16, v16, v16 quad_perm:[2,3,0,1] row_mask:0xf bank_mask:0xf
	s_nop 1
	v_add_f32_dpp v16, v16, v16 row_half_mirror row_mask:0xf bank_mask:0xf
	s_nop 1
	v_add_f32_dpp v16, v16, v16 row_mirror row_mask:0xf bank_mask:0xf
	v_mov_b32_e32 v17, v16
	s_nop 1
	v_permlane16_swap_b32_e32 v16, v17
	v_add_f32_e32 v16, v16, v17
	v_mov_b32_e32 v17, v16
	s_nop 1
	v_permlane32_swap_b32_e32 v16, v17
	s_and_saveexec_b64 s[20:21], s[40:41]
	s_cbranch_execz .LBB0_1268
; #define GASF __attribute__((address_space(1)))
; __device__ __forceinline__ void resid_rows(const float* xf_, bf16_t* XB_, const bf16_t* Y_, const float* gain_, float* R_, float* outf_, int rows, int gw, int NGW, int lane) {
;     ...
;             ss = wave_sum(ss);
;             if (lane == 0) ((GASF float*)R_)[row] = 1.0f / sqrtf(ss * (1.f / DM) + EPS); }
	v_add_f32_e32 v16, v16, v17
	v_fmamk_f32 v16, v16, 0x3a800000, v204
	v_mul_f32_e32 v17, 0x4f800000, v16
	v_cmp_gt_f32_e32 vcc, s81, v16
	s_nop 1
	v_cndmask_b32_e32 v16, v16, v17, vcc
	v_sqrt_f32_e32 v17, v16
	s_nop 0
	v_add_u32_e32 v18, -1, v17
	v_fma_f32 v20, -v18, v17, v16
	v_add_u32_e32 v19, 1, v17
	v_cmp_ge_f32_e64 s[42:43], 0, v20
	s_nop 1
	v_cndmask_b32_e64 v18, v17, v18, s[42:43]
	v_fma_f32 v17, -v19, v17, v16
	v_cmp_lt_f32_e64 s[42:43], 0, v17
	s_nop 1
	v_cndmask_b32_e64 v17, v18, v19, s[42:43]
	v_mul_f32_e32 v18, 0x37800000, v17
	v_cndmask_b32_e32 v17, v17, v18, vcc
	v_cmp_class_f32_e32 vcc, v16, v205
	s_nop 1
	v_cndmask_b32_e32 v16, v17, v16, vcc
	v_div_scale_f32 v17, s[28:29], v16, v16, 1.0
	v_rcp_f32_e32 v18, v17
	s_nop 0
	v_fma_f32 v19, -v17, v18, 1.0
	v_fmac_f32_e32 v18, v19, v18
	v_div_scale_f32 v19, vcc, 1.0, v16, 1.0
	v_mul_f32_e32 v20, v19, v18
	v_fma_f32 v21, -v17, v20, v19
	v_fmac_f32_e32 v20, v21, v18
	v_fma_f32 v17, -v17, v20, v19
	v_div_fmas_f32 v17, v17, v18, v20
	v_div_fixup_f32 v16, v17, v16, 1.0
	global_store_dword v175, v16, s[12:13]
	s_branch .LBB0_1268
